# grid barrier: the 8 XCD leaders poll their local arrival counter without s_sleep
# speedup vs baseline: 1.0035x; 1.0002x over previous
.Lnb_spin_loc_r:
	global_load_dword v6, v7, s[10:11] offset:1024 sc1
	s_waitcnt vmcnt(0)
	v_cmp_le_u32_e32 vcc, v10, v6
	s_cbranch_vccnz .Lnb_loc_done_r
	s_nop 0
	s_add_i32 s3, s3, 1
	s_cmp_lt_u32 s3, 0x40000
	s_cbranch_scc1 .Lnb_spin_loc_r

.Lnb_spin_loc_m:
	global_load_dword v6, v7, s[10:11] offset:1024 sc1
	s_waitcnt vmcnt(0)
	v_cmp_le_u32_e32 vcc, v10, v6
	s_cbranch_vccnz .Lnb_loc_done_m
	s_nop 0
	s_add_i32 s2, s2, 1
	s_cmp_lt_u32 s2, 0x40000
	s_cbranch_scc1 .Lnb_spin_loc_m
